# speedup vs baseline: 1.0143x; 1.0010x over previous
; #define SCHED() __builtin_amdgcn_sched_barrier(0)
; #define DSR(dst, addr, off) asm volatile("ds_read_b128 %0, %1 offset:%2" : "=&v"(dst) : "v"(addr), "n"(off) : "memory")
; #define LGKM(n) asm volatile("s_waitcnt lgkmcnt(%0)" ::"n"(n) : "memory")
; #define DSR(dst, addr, off) asm volatile("ds_read_b128 %0, %1 offset:%2" : "=&v"(dst) : "v"(addr), "n"(off) : "memory")
; #define LGKM(n) asm volatile("s_waitcnt lgkmcnt(%0)" ::"n"(n) : "memory")
; __device__ __forceinline__ void attn_phase(char* shm, const Params& p, const u16* __restrict__ qb, const u16* __restrict__ kb,
;                                            const u16* __restrict__ vT, u16* __restrict__ attn) {
;     ...
;         const float df = (float)(kt * 64 + u * 32 + 4 * hh - qpos);
;         bf16x8 P[2][2];
;         bf16x8 kf[2], qf[2];
;         DSR(kf[0], kb_ + kL0, u * 8192); DSR(qf[0], qaddr, 0);
; #pragma unroll
;         for (int c = 0; c < 2; ++c) {
;           f32x16 Sx;
; #pragma unroll
;           for (int i = 0; i < 16; ++i) Sx[i] = -sl2 * fabsf(df + (float)((i & 3) + 8 * (i >> 2)));
; #pragma unroll
;           for (int ks = 0; ks < 4; ++ks) {
;             const int f = c * 4 + ks;
;             if (f < 7) {
;               DSR(kf[(f + 1) & 1], kb_ + (kL0 ^ ((((f + 1) >> 2) * 8 + ((f + 1) & 3) * 2) << 4)), u * 8192);
;               DSR(qf[(f + 1) & 1], qaddr, (f + 1) * 1024);
;               LGKM(2);
;             } else LGKM(0);
;             SCHED();
;             Sx = __builtin_amdgcn_mfma_f32_32x32x16_bf16(kf[f & 1], qf[f & 1], Sx, 0, 0, 0);
;             SCHED();
;           }
;           float pv[16];
; #pragma unroll
;           for (int i = 0; i < 16; ++i) { pv[i] = __builtin_amdgcn_exp2f(Sx[i]); lsum[c] += pv[i]; }
; #pragma unroll
;           for (int a = 0; a < 2; ++a) {
;             i32x4 t4;
; #pragma unroll
;             for (int i = 0; i < 4; ++i) t4[i] = pk_bf16(pv[a * 8 + 2 * i], pv[a * 8 + 2 * i + 1]);
;             P[c][a] = __builtin_bit_cast(bf16x8, t4);
;           }
;         }
.LBB0_299:
	v_cvt_f32_i32_e32 v128, v205
	v_add_u32_e32 v160, s44, v188
	ds_read_b128 v[206:209], v160 offset:0
	ds_read_b128 v[210:213], v185 offset:0
	v_add_u32_e32 v214, s44, v190
	ds_read_b128 v[218:221], v214 offset:0
	ds_read_b128 v[222:225], v185 offset:0x400
	v_add_u32_e32 v215, s44, v191
	ds_read_b128 v[242:245], v215 offset:0
	ds_read_b128 v[246:249], v185 offset:0x800
	v_add_f32_e32 v129, 1.0, v128
	v_pk_add_f32 v[130:131], v[128:129], s[12:13] op_sel_hi:[0,1]
	v_pk_add_f32 v[132:133], v[128:129], s[14:15] op_sel_hi:[0,1]
	v_pk_add_f32 v[134:135], v[128:129], s[20:21] op_sel_hi:[0,1]
	v_pk_add_f32 v[136:137], v[128:129], s[22:23] op_sel_hi:[0,1]
	v_pk_add_f32 v[138:139], v[128:129], s[24:25] op_sel_hi:[0,1]
	v_pk_add_f32 v[140:141], v[128:129], s[26:27] op_sel_hi:[0,1]
	v_pk_add_f32 v[142:143], v[128:129], s[28:29] op_sel_hi:[0,1]
	v_and_b32_e32 v131, 0x7fffffff, v131
	v_and_b32_e32 v130, 0x7fffffff, v130
	v_and_b32_e32 v133, 0x7fffffff, v133
	v_and_b32_e32 v132, 0x7fffffff, v132
	v_and_b32_e32 v135, 0x7fffffff, v135
	v_and_b32_e32 v134, 0x7fffffff, v134
	v_and_b32_e32 v137, 0x7fffffff, v137
	v_and_b32_e32 v136, 0x7fffffff, v136
	v_and_b32_e32 v139, 0x7fffffff, v139
	v_and_b32_e32 v138, 0x7fffffff, v138
	v_and_b32_e32 v141, 0x7fffffff, v141
	v_and_b32_e32 v140, 0x7fffffff, v140
	v_and_b32_e32 v143, 0x7fffffff, v143
	v_and_b32_e32 v142, 0x7fffffff, v142
	v_and_b32_e32 v128, 0x7fffffff, v128
	v_and_b32_e32 v129, 0x7fffffff, v129
	s_add_i32 s0, s44, 0x4000
	v_pk_mul_f32 v[142:143], v[178:179], v[142:143]
	v_pk_mul_f32 v[140:141], v[178:179], v[140:141]
	v_pk_mul_f32 v[138:139], v[178:179], v[138:139]
	v_pk_mul_f32 v[136:137], v[178:179], v[136:137]
	v_pk_mul_f32 v[134:135], v[178:179], v[134:135]
	v_pk_mul_f32 v[132:133], v[178:179], v[132:133]
	v_pk_mul_f32 v[130:131], v[178:179], v[130:131]
	v_pk_mul_f32 v[128:129], v[170:171], v[128:129]
	s_nop 1
	s_waitcnt lgkmcnt(4)
	v_readfirstlane_b32 s88, v128
	s_cmp_gt_u32 s88, 0xc35c0000
	s_cselect_b32 s89, 1, 0
	s_mov_b32 s90, 0
	v_mfma_f32_32x32x16_bf16 v[144:159], v[206:209], v[210:213], v[128:143]
	v_add_u32_e32 v226, s44, v192
	ds_read_b128 v[206:209], v226 offset:0
	ds_read_b128 v[210:213], v185 offset:0xc00
	s_waitcnt lgkmcnt(4)
	v_mfma_f32_32x32x16_bf16 v[144:159], v[218:221], v[222:225], v[144:159]
	v_add_u32_e32 v227, s44, v193
	ds_read_b128 v[218:221], v227 offset:0
	ds_read_b128 v[222:225], v185 offset:0x1000
	s_waitcnt lgkmcnt(4)
	v_mfma_f32_32x32x16_bf16 v[144:159], v[242:245], v[246:249], v[144:159]
	v_add_u32_e32 v229, s44, v194
	ds_read_b128 v[242:245], v229 offset:0
	ds_read_b128 v[246:249], v185 offset:0x1400
	s_waitcnt lgkmcnt(4)
	v_mfma_f32_32x32x16_bf16 v[144:159], v[206:209], v[210:213], v[144:159]
	v_add_u32_e32 v230, s44, v195
	ds_read_b128 v[206:209], v230 offset:0
	ds_read_b128 v[210:213], v185 offset:0x1800
	s_nop 11
	s_cmp_eq_u32 s89, 0
	s_cbranch_scc1 .Lattn_exp_normal_0_0
	v_max3_f32 v240, v144, v145, v146
	v_max3_f32 v240, v240, v147, v148
	v_max3_f32 v240, v240, v149, v150
	v_max3_f32 v240, v240, v151, v152
	v_max3_f32 v240, v240, v153, v154
	v_max3_f32 v240, v240, v155, v156
	v_max3_f32 v240, v240, v157, v158
	v_max_f32_e32 v240, v240, v159
	v_cmp_ngt_f32_e32 vcc, 0xc3180000, v240
	s_and_b64 vcc, exec, vcc
	s_cbranch_vccnz .Lattn_exp_normal_0_0
	v_mov_b32_e32 v144, 0
	v_mov_b32_e32 v145, 0
	v_mov_b32_e32 v146, 0
	v_mov_b32_e32 v147, 0
	v_mov_b32_e32 v148, 0
	v_mov_b32_e32 v149, 0
	v_mov_b32_e32 v150, 0
	v_mov_b32_e32 v151, 0
	s_add_i32 s90, s90, 1
	s_branch .Lattn_exp_done_0_0

; #define SCHED() __builtin_amdgcn_sched_barrier(0)
; #define DSR(dst, addr, off) asm volatile("ds_read_b128 %0, %1 offset:%2" : "=&v"(dst) : "v"(addr), "n"(off) : "memory")
; #define LGKM(n) asm volatile("s_waitcnt lgkmcnt(%0)" ::"n"(n) : "memory")
; #define DSR(dst, addr, off) asm volatile("ds_read_b128 %0, %1 offset:%2" : "=&v"(dst) : "v"(addr), "n"(off) : "memory")
; #define LGKM(n) asm volatile("s_waitcnt lgkmcnt(%0)" ::"n"(n) : "memory")
; __device__ __forceinline__ void attn_phase(char* shm, const Params& p, const u16* __restrict__ qb, const u16* __restrict__ kb,
;                                            const u16* __restrict__ vT, u16* __restrict__ attn) {
;     ...
;           for (int i = 0; i < 16; ++i) Sx[i] = -sl2 * fabsf(df + (float)((i & 3) + 8 * (i >> 2)));
; #pragma unroll
;           for (int ks = 0; ks < 4; ++ks) {
;             const int f = c * 4 + ks;
;             if (f < 7) {
;               DSR(kf[(f + 1) & 1], kb_ + (kL0 ^ ((((f + 1) >> 2) * 8 + ((f + 1) & 3) * 2) << 4)), u * 8192);
;               DSR(qf[(f + 1) & 1], qaddr, (f + 1) * 1024);
;               LGKM(2);
;             } else LGKM(0);
;             SCHED();
;             Sx = __builtin_amdgcn_mfma_f32_32x32x16_bf16(kf[f & 1], qf[f & 1], Sx, 0, 0, 0);
;             SCHED();
;           }
.Lattn_exp_done_0_0:
	s_waitcnt lgkmcnt(4)
	v_mfma_f32_32x32x16_bf16 v[128:143], v[218:221], v[222:225], v[128:143]
	v_add_u32_e32 v232, s44, v196
	ds_read_b128 v[218:221], v232 offset:0
	ds_read_b128 v[222:225], v185 offset:0x1c00
	s_waitcnt lgkmcnt(4)
	v_mfma_f32_32x32x16_bf16 v[128:143], v[242:245], v[246:249], v[128:143]
	s_waitcnt lgkmcnt(2)
	v_mfma_f32_32x32x16_bf16 v[128:143], v[206:209], v[210:213], v[128:143]
	s_waitcnt lgkmcnt(0)
	v_mfma_f32_32x32x16_bf16 v[128:143], v[218:221], v[222:225], v[128:143]
	s_nop 11
	s_cmp_eq_u32 s89, 0
	s_cbranch_scc1 .Lattn_exp_normal_0_1
	v_max3_f32 v240, v128, v129, v130
	v_max3_f32 v240, v240, v131, v132
	v_max3_f32 v240, v240, v133, v134
	v_max3_f32 v240, v240, v135, v136
	v_max3_f32 v240, v240, v137, v138
	v_max3_f32 v240, v240, v139, v140
	v_max3_f32 v240, v240, v141, v142
	v_max_f32_e32 v240, v240, v143
	v_cmp_ngt_f32_e32 vcc, 0xc3180000, v240
	s_and_b64 vcc, exec, vcc
	s_cbranch_vccnz .Lattn_exp_normal_0_1
	v_add_u32_e32 v152, s0, v189
	ds_read_b128 v[136:139], v152 offset:0
	ds_read_b128 v[140:143], v152 offset:0x1000
	v_mov_b32_e32 v128, 0
	v_mov_b32_e32 v129, 0
	v_mov_b32_e32 v130, 0
	v_mov_b32_e32 v131, 0
	v_mov_b32_e32 v132, 0
	v_mov_b32_e32 v133, 0
	v_mov_b32_e32 v134, 0
	v_mov_b32_e32 v135, 0
	s_add_i32 s90, s90, 1
	s_branch .Lattn_exp_done_0_1

; #define SCHED() __builtin_amdgcn_sched_barrier(0)
; #define DSR(dst, addr, off) asm volatile("ds_read_b128 %0, %1 offset:%2" : "=&v"(dst) : "v"(addr), "n"(off) : "memory")
; __device__ __forceinline__ void attn_phase(char* shm, const Params& p, const u16* __restrict__ qb, const u16* __restrict__ kb,
;                                            const u16* __restrict__ vT, u16* __restrict__ attn) {
;     ...
; #pragma unroll
;       for (int u = 0; u < 2; ++u) {
;         const float df = (float)(kt * 64 + u * 32 + 4 * hh - qpos);
;         bf16x8 P[2][2];
;         bf16x8 kf[2], qf[2];
;         DSR(kf[0], kb_ + kL0, u * 8192); DSR(qf[0], qaddr, 0);
; #pragma unroll
;         for (int c = 0; c < 2; ++c) {
;           f32x16 Sx;
; #pragma unroll
;           for (int i = 0; i < 16; ++i) Sx[i] = -sl2 * fabsf(df + (float)((i & 3) + 8 * (i >> 2)));
; #pragma unroll
;           for (int ks = 0; ks < 4; ++ks) {
;             const int f = c * 4 + ks;
;             if (f < 7) {
;               DSR(kf[(f + 1) & 1], kb_ + (kL0 ^ ((((f + 1) >> 2) * 8 + ((f + 1) & 3) * 2) << 4)), u * 8192);
;               DSR(qf[(f + 1) & 1], qaddr, (f + 1) * 1024);
;               LGKM(2);
;             } else LGKM(0);
;             SCHED();
;             Sx = __builtin_amdgcn_mfma_f32_32x32x16_bf16(kf[f & 1], qf[f & 1], Sx, 0, 0, 0);
;             SCHED();
;           }
;           float pv[16];
; #pragma unroll
;           for (int i = 0; i < 16; ++i) { pv[i] = __builtin_amdgcn_exp2f(Sx[i]); lsum[c] += pv[i]; }
; #pragma unroll
;           for (int a = 0; a < 2; ++a) {
;             i32x4 t4;
; #pragma unroll
;             for (int i = 0; i < 4; ++i) t4[i] = pk_bf16(pv[a * 8 + 2 * i], pv[a * 8 + 2 * i + 1]);
;             P[c][a] = __builtin_bit_cast(bf16x8, t4);
;           }
;         }
;         bf16x8 vf[2];
;         DSR(vf[0], vb_ + (vM0 ^ ((u * 4) << 4)), 0);
; #pragma unroll
;         for (int g = 0; g < 8; ++g) {
;           const int a = g >> 2, t = g & 3;
;           if (g < 7) { DSR(vf[(g + 1) & 1], vb_ + (vM0 ^ ((u * 4 + ((g + 1) >> 2) * 2) << 4)), ((g + 1) & 3) * 4096); LGKM(1); }
;           else LGKM(0);
;           SCHED();
;           O[0][t] = __builtin_amdgcn_mfma_f32_32x32x16_bf16(vf[g & 1], P[0][a], O[0][t], 0, 0, 0);
;           O[1][t] = __builtin_amdgcn_mfma_f32_32x32x16_bf16(vf[g & 1], P[1][a], O[1][t], 0, 0, 0);
;           SCHED();
;         }
.Lattn_exp_done_0_1:
	s_waitcnt lgkmcnt(1)
	s_cmp_eq_u32 s90, 2
	s_cbranch_scc1 .Lattn_pv_zero_0
	v_mfma_f32_32x32x16_bf16 v[112:127], v[136:139], v[144:147], v[112:127]
	v_mfma_f32_32x32x16_bf16 v[96:111], v[136:139], v[128:131], v[96:111]
	ds_read_b128 v[136:139], v152 offset:0x2000
	s_waitcnt lgkmcnt(1)
	v_mfma_f32_32x32x16_bf16 v[80:95], v[140:143], v[144:147], v[80:95]
	v_mfma_f32_32x32x16_bf16 v[64:79], v[140:143], v[128:131], v[64:79]
	ds_read_b128 v[140:143], v152 offset:0x3000
	s_waitcnt lgkmcnt(1)
	v_mfma_f32_32x32x16_bf16 v[48:63], v[136:139], v[144:147], v[48:63]
	v_mfma_f32_32x32x16_bf16 v[16:31], v[136:139], v[128:131], v[16:31]
	v_add_u32_e32 v152, s0, v197
	ds_read_b128 v[136:139], v152 offset:0
	s_waitcnt lgkmcnt(1)
	v_mfma_f32_32x32x16_bf16 v[32:47], v[140:143], v[144:147], v[32:47]
	v_mfma_f32_32x32x16_bf16 v[0:15], v[140:143], v[128:131], v[0:15]
	ds_read_b128 v[128:131], v152 offset:0x1000
	s_waitcnt lgkmcnt(1)
	v_mfma_f32_32x32x16_bf16 v[112:127], v[136:139], v[148:151], v[112:127]
	v_mfma_f32_32x32x16_bf16 v[96:111], v[136:139], v[132:135], v[96:111]
	ds_read_b128 v[136:139], v152 offset:0x2000
	s_waitcnt lgkmcnt(1)
	v_mfma_f32_32x32x16_bf16 v[80:95], v[128:131], v[148:151], v[80:95]
	v_mfma_f32_32x32x16_bf16 v[64:79], v[128:131], v[132:135], v[64:79]
	ds_read_b128 v[128:131], v152 offset:0x3000
	s_waitcnt lgkmcnt(1)
	v_mfma_f32_32x32x16_bf16 v[48:63], v[136:139], v[148:151], v[48:63]
	v_mfma_f32_32x32x16_bf16 v[16:31], v[136:139], v[132:135], v[16:31]
	s_waitcnt lgkmcnt(0)
	v_mfma_f32_32x32x16_bf16 v[32:47], v[128:131], v[148:151], v[32:47]
	v_mfma_f32_32x32x16_bf16 v[0:15], v[128:131], v[132:135], v[0:15]
.Lattn_pv_zero_0:
	s_waitcnt lgkmcnt(0)
	v_add_u32_e32 v128, 32, v205
	v_cvt_f32_i32_e32 v128, v128
	ds_read_b128 v[206:209], v160 offset:0x2000
	ds_read_b128 v[210:213], v185 offset:0
	ds_read_b128 v[218:221], v214 offset:0x2000
	ds_read_b128 v[222:225], v185 offset:0x400
	ds_read_b128 v[242:245], v215 offset:0x2000
	ds_read_b128 v[246:249], v185 offset:0x800
	v_add_f32_e32 v129, 1.0, v128
	v_pk_add_f32 v[130:131], v[128:129], s[12:13] op_sel_hi:[0,1]
	v_pk_add_f32 v[132:133], v[128:129], s[14:15] op_sel_hi:[0,1]
	v_pk_add_f32 v[134:135], v[128:129], s[20:21] op_sel_hi:[0,1]
	v_pk_add_f32 v[136:137], v[128:129], s[22:23] op_sel_hi:[0,1]
	v_pk_add_f32 v[138:139], v[128:129], s[24:25] op_sel_hi:[0,1]
	v_pk_add_f32 v[140:141], v[128:129], s[26:27] op_sel_hi:[0,1]
	v_pk_add_f32 v[142:143], v[128:129], s[28:29] op_sel_hi:[0,1]
	v_and_b32_e32 v131, 0x7fffffff, v131
	v_and_b32_e32 v130, 0x7fffffff, v130
	v_and_b32_e32 v133, 0x7fffffff, v133
	v_and_b32_e32 v132, 0x7fffffff, v132
	v_and_b32_e32 v135, 0x7fffffff, v135
	v_and_b32_e32 v134, 0x7fffffff, v134
	v_and_b32_e32 v137, 0x7fffffff, v137
	v_and_b32_e32 v136, 0x7fffffff, v136
	v_and_b32_e32 v139, 0x7fffffff, v139
	v_and_b32_e32 v138, 0x7fffffff, v138
	v_and_b32_e32 v141, 0x7fffffff, v141
	v_and_b32_e32 v140, 0x7fffffff, v140
	v_and_b32_e32 v143, 0x7fffffff, v143
	v_and_b32_e32 v142, 0x7fffffff, v142
	v_and_b32_e32 v128, 0x7fffffff, v128
	v_and_b32_e32 v129, 0x7fffffff, v129
	v_pk_mul_f32 v[142:143], v[178:179], v[142:143]
	v_pk_mul_f32 v[140:141], v[178:179], v[140:141]
	v_pk_mul_f32 v[138:139], v[178:179], v[138:139]
	v_pk_mul_f32 v[136:137], v[178:179], v[136:137]
	v_pk_mul_f32 v[134:135], v[178:179], v[134:135]
	v_pk_mul_f32 v[132:133], v[178:179], v[132:133]
	v_pk_mul_f32 v[130:131], v[178:179], v[130:131]
	v_pk_mul_f32 v[128:129], v[170:171], v[128:129]
	s_nop 1
	s_waitcnt lgkmcnt(4)
	v_readfirstlane_b32 s88, v128
	s_cmp_gt_u32 s88, 0xc35c0000
	s_cselect_b32 s89, 1, 0
	s_mov_b32 s90, 0
	v_mfma_f32_32x32x16_bf16 v[144:159], v[206:209], v[210:213], v[128:143]
	ds_read_b128 v[206:209], v226 offset:0x2000
	ds_read_b128 v[210:213], v185 offset:0xc00
	s_waitcnt lgkmcnt(4)
	v_mfma_f32_32x32x16_bf16 v[144:159], v[218:221], v[222:225], v[144:159]
	ds_read_b128 v[218:221], v227 offset:0x2000
	ds_read_b128 v[222:225], v185 offset:0x1000
	s_waitcnt lgkmcnt(4)
	v_mfma_f32_32x32x16_bf16 v[144:159], v[242:245], v[246:249], v[144:159]
	ds_read_b128 v[242:245], v229 offset:0x2000
	ds_read_b128 v[246:249], v185 offset:0x1400
	s_waitcnt lgkmcnt(4)
	v_mfma_f32_32x32x16_bf16 v[144:159], v[206:209], v[210:213], v[144:159]
	ds_read_b128 v[206:209], v230 offset:0x2000
	ds_read_b128 v[210:213], v185 offset:0x1800
	s_nop 11
	s_cmp_eq_u32 s89, 0
	s_cbranch_scc1 .Lattn_exp_normal_1_0
	v_max3_f32 v240, v144, v145, v146
	v_max3_f32 v240, v240, v147, v148
	v_max3_f32 v240, v240, v149, v150
	v_max3_f32 v240, v240, v151, v152
	v_max3_f32 v240, v240, v153, v154
	v_max3_f32 v240, v240, v155, v156
	v_max3_f32 v240, v240, v157, v158
	v_max_f32_e32 v240, v240, v159
	v_cmp_ngt_f32_e32 vcc, 0xc3180000, v240
	s_and_b64 vcc, exec, vcc
	s_cbranch_vccnz .Lattn_exp_normal_1_0
	v_mov_b32_e32 v144, 0
	v_mov_b32_e32 v145, 0
	v_mov_b32_e32 v146, 0
	v_mov_b32_e32 v147, 0
	v_mov_b32_e32 v148, 0
	v_mov_b32_e32 v149, 0
	v_mov_b32_e32 v150, 0
	v_mov_b32_e32 v151, 0
	s_add_i32 s90, s90, 1
	s_branch .Lattn_exp_done_1_0

; #define SCHED() __builtin_amdgcn_sched_barrier(0)
; #define DSR(dst, addr, off) asm volatile("ds_read_b128 %0, %1 offset:%2" : "=&v"(dst) : "v"(addr), "n"(off) : "memory")
; #define LGKM(n) asm volatile("s_waitcnt lgkmcnt(%0)" ::"n"(n) : "memory")
; #define DSR(dst, addr, off) asm volatile("ds_read_b128 %0, %1 offset:%2" : "=&v"(dst) : "v"(addr), "n"(off) : "memory")
; #define LGKM(n) asm volatile("s_waitcnt lgkmcnt(%0)" ::"n"(n) : "memory")
; __device__ __forceinline__ void attn_phase(char* shm, const Params& p, const u16* __restrict__ qb, const u16* __restrict__ kb,
;                                            const u16* __restrict__ vT, u16* __restrict__ attn) {
;     ...
;         for (int c = 0; c < 2; ++c) {
;           f32x16 Sx;
; #pragma unroll
;           for (int i = 0; i < 16; ++i) Sx[i] = -sl2 * fabsf(df + (float)((i & 3) + 8 * (i >> 2)));
; #pragma unroll
;           for (int ks = 0; ks < 4; ++ks) {
;             const int f = c * 4 + ks;
;             if (f < 7) {
;               DSR(kf[(f + 1) & 1], kb_ + (kL0 ^ ((((f + 1) >> 2) * 8 + ((f + 1) & 3) * 2) << 4)), u * 8192);
;               DSR(qf[(f + 1) & 1], qaddr, (f + 1) * 1024);
;               LGKM(2);
;             } else LGKM(0);
;             SCHED();
;             Sx = __builtin_amdgcn_mfma_f32_32x32x16_bf16(kf[f & 1], qf[f & 1], Sx, 0, 0, 0);
;             SCHED();
;           }
;           float pv[16];
; #pragma unroll
;           for (int i = 0; i < 16; ++i) { pv[i] = __builtin_amdgcn_exp2f(Sx[i]); lsum[c] += pv[i]; }
; #pragma unroll
;           for (int a = 0; a < 2; ++a) {
;             i32x4 t4;
; #pragma unroll
;             for (int i = 0; i < 4; ++i) t4[i] = pk_bf16(pv[a * 8 + 2 * i], pv[a * 8 + 2 * i + 1]);
;             P[c][a] = __builtin_bit_cast(bf16x8, t4);
;           }
;         }
.Lattn_exp_done_1_0:
	s_waitcnt lgkmcnt(4)
	v_mfma_f32_32x32x16_bf16 v[128:143], v[218:221], v[222:225], v[128:143]
	ds_read_b128 v[218:221], v232 offset:0x2000
	ds_read_b128 v[222:225], v185 offset:0x1c00
	s_waitcnt lgkmcnt(4)
	v_mfma_f32_32x32x16_bf16 v[128:143], v[242:245], v[246:249], v[128:143]
	s_waitcnt lgkmcnt(2)
	v_mfma_f32_32x32x16_bf16 v[128:143], v[206:209], v[210:213], v[128:143]
	s_waitcnt lgkmcnt(0)
	v_mfma_f32_32x32x16_bf16 v[128:143], v[218:221], v[222:225], v[128:143]
	s_nop 11
	s_cmp_eq_u32 s89, 0
	s_cbranch_scc1 .Lattn_exp_normal_1_1
	v_max3_f32 v240, v128, v129, v130
	v_max3_f32 v240, v240, v131, v132
	v_max3_f32 v240, v240, v133, v134
	v_max3_f32 v240, v240, v135, v136
	v_max3_f32 v240, v240, v137, v138
	v_max3_f32 v240, v240, v139, v140
	v_max3_f32 v240, v240, v141, v142
	v_max_f32_e32 v240, v240, v143
	v_cmp_ngt_f32_e32 vcc, 0xc3180000, v240
	s_and_b64 vcc, exec, vcc
	s_cbranch_vccnz .Lattn_exp_normal_1_1
	v_add_u32_e32 v152, s0, v198
	ds_read_b128 v[136:139], v152 offset:0
	ds_read_b128 v[140:143], v152 offset:0x1000
	v_mov_b32_e32 v128, 0
	v_mov_b32_e32 v129, 0
	v_mov_b32_e32 v130, 0
	v_mov_b32_e32 v131, 0
	v_mov_b32_e32 v132, 0
	v_mov_b32_e32 v133, 0
	v_mov_b32_e32 v134, 0
	v_mov_b32_e32 v135, 0
	s_add_i32 s90, s90, 1
	s_branch .Lattn_exp_done_1_1

; #define SCHED() __builtin_amdgcn_sched_barrier(0)
; #define DSR(dst, addr, off) asm volatile("ds_read_b128 %0, %1 offset:%2" : "=&v"(dst) : "v"(addr), "n"(off) : "memory")
; #define LGKM(n) asm volatile("s_waitcnt lgkmcnt(%0)" ::"n"(n) : "memory")
; #define DSR(dst, addr, off) asm volatile("ds_read_b128 %0, %1 offset:%2" : "=&v"(dst) : "v"(addr), "n"(off) : "memory")
; #define LGKM(n) asm volatile("s_waitcnt lgkmcnt(%0)" ::"n"(n) : "memory")
; __device__ __forceinline__ void attn_phase(char* shm, const Params& p, const u16* __restrict__ qb, const u16* __restrict__ kb,
;                                            const u16* __restrict__ vT, u16* __restrict__ attn) {
;     ...
;         bf16x8 vf[2];
;         DSR(vf[0], vb_ + (vM0 ^ ((u * 4) << 4)), 0);
; #pragma unroll
;         for (int g = 0; g < 8; ++g) {
;           const int a = g >> 2, t = g & 3;
;           if (g < 7) { DSR(vf[(g + 1) & 1], vb_ + (vM0 ^ ((u * 4 + ((g + 1) >> 2) * 2) << 4)), ((g + 1) & 3) * 4096); LGKM(1); }
;           else LGKM(0);
;           SCHED();
;           O[0][t] = __builtin_amdgcn_mfma_f32_32x32x16_bf16(vf[g & 1], P[0][a], O[0][t], 0, 0, 0);
;           O[1][t] = __builtin_amdgcn_mfma_f32_32x32x16_bf16(vf[g & 1], P[1][a], O[1][t], 0, 0, 0);
;           SCHED();
;         }
.Lattn_exp_done_1_1:
	s_waitcnt lgkmcnt(1)
	s_cmp_eq_u32 s90, 2
	s_cbranch_scc1 .Lattn_pv_zero_1
	v_mfma_f32_32x32x16_bf16 v[112:127], v[136:139], v[144:147], v[112:127]
	v_mfma_f32_32x32x16_bf16 v[96:111], v[136:139], v[128:131], v[96:111]
	ds_read_b128 v[136:139], v152 offset:0x2000
	s_waitcnt lgkmcnt(1)
	v_mfma_f32_32x32x16_bf16 v[80:95], v[140:143], v[144:147], v[80:95]
	v_mfma_f32_32x32x16_bf16 v[64:79], v[140:143], v[128:131], v[64:79]
	ds_read_b128 v[140:143], v152 offset:0x3000
	s_waitcnt lgkmcnt(1)
	v_mfma_f32_32x32x16_bf16 v[48:63], v[136:139], v[144:147], v[48:63]
	v_mfma_f32_32x32x16_bf16 v[16:31], v[136:139], v[128:131], v[16:31]
	v_add_u32_e32 v152, s0, v199
	ds_read_b128 v[136:139], v152 offset:0
	s_waitcnt lgkmcnt(1)
	v_mfma_f32_32x32x16_bf16 v[32:47], v[140:143], v[144:147], v[32:47]
	v_mfma_f32_32x32x16_bf16 v[0:15], v[140:143], v[128:131], v[0:15]
	ds_read_b128 v[128:131], v152 offset:0x1000
	s_waitcnt lgkmcnt(1)
	v_mfma_f32_32x32x16_bf16 v[112:127], v[136:139], v[148:151], v[112:127]
	v_mfma_f32_32x32x16_bf16 v[96:111], v[136:139], v[132:135], v[96:111]
	ds_read_b128 v[136:139], v152 offset:0x2000
	s_waitcnt lgkmcnt(1)
	v_mfma_f32_32x32x16_bf16 v[80:95], v[128:131], v[148:151], v[80:95]
	v_mfma_f32_32x32x16_bf16 v[64:79], v[128:131], v[132:135], v[64:79]
	ds_read_b128 v[128:131], v152 offset:0x3000
	s_waitcnt lgkmcnt(1)
	v_mfma_f32_32x32x16_bf16 v[48:63], v[136:139], v[148:151], v[48:63]
	v_mfma_f32_32x32x16_bf16 v[16:31], v[136:139], v[132:135], v[16:31]
	s_waitcnt lgkmcnt(0)
	v_mfma_f32_32x32x16_bf16 v[32:47], v[128:131], v[148:151], v[32:47]
	v_mfma_f32_32x32x16_bf16 v[0:15], v[128:131], v[132:135], v[0:15]
